# residual GEMM epilogue fast path with the next block's residual loads issued one block ahead
# speedup vs baseline: 1.0036x; 1.0036x over previous
.LBB0_104:
	s_or_b64 exec, exec, s[60:61]
	s_and_saveexec_b64 s[60:61], s[58:59]
	s_cbranch_execz .LBB0_106
	v_mov_b32_e32 v230, v144
	v_mov_b32_e32 v231, v145
	v_mov_b32_e32 v232, v140
	v_mov_b32_e32 v233, v141
	v_mov_b32_e32 v234, v166
	v_mov_b32_e32 v235, v167
	v_mov_b32_e32 v236, v230
	v_mov_b32_e32 v237, v231
	global_load_dwordx4 v[194:197], v[236:237], off
	global_load_dwordx4 v[198:201], v[236:237], off offset:64
	v_mov_b32_e32 v236, v234
	v_mov_b32_e32 v237, v235
	global_load_dwordx4 v[210:213], v[236:237], off
	global_load_dwordx4 v[214:217], v[236:237], off offset:64
	v_add_co_u32_e32 v236, vcc, 0x200, v234
	v_addc_co_u32_e32 v237, vcc, 0, v235, vcc
	global_load_dwordx4 v[218:221], v[236:237], off
	global_load_dwordx4 v[222:225], v[236:237], off offset:64
	v_add_co_u32_e32 v236, vcc, 0x200, v230
	v_addc_co_u32_e32 v237, vcc, 0, v231, vcc
	global_load_dwordx4 v[202:205], v[236:237], off
	global_load_dwordx4 v[206:209], v[236:237], off offset:64
	v_mov_b32_e32 v244, v232
	v_mov_b32_e32 v245, v233
	s_waitcnt vmcnt(2)
	v_pk_fma_f32 v[196:197], v[126:127], v[212:213], v[196:197]
	v_pk_fma_f32 v[194:195], v[124:125], v[210:211], v[194:195]
	global_store_dwordx4 v[244:245], v[194:197], off
	v_pk_fma_f32 v[200:201], v[122:123], v[216:217], v[200:201]
	v_pk_fma_f32 v[198:199], v[120:121], v[214:215], v[198:199]
	global_store_dwordx4 v[244:245], v[198:201], off offset:64
	v_add_co_u32_e32 v236, vcc, 0x10000, v230
	v_addc_co_u32_e32 v237, vcc, 0, v231, vcc
	global_load_dwordx4 v[194:197], v[236:237], off
	global_load_dwordx4 v[198:201], v[236:237], off offset:64
	v_add_co_u32_e32 v244, vcc, 0x200, v232
	v_addc_co_u32_e32 v245, vcc, 0, v233, vcc
	s_waitcnt vmcnt(4)
	v_pk_fma_f32 v[204:205], v[118:119], v[220:221], v[204:205]
	v_pk_fma_f32 v[202:203], v[116:117], v[218:219], v[202:203]
	global_store_dwordx4 v[244:245], v[202:205], off
	v_pk_fma_f32 v[208:209], v[114:115], v[224:225], v[208:209]
	v_pk_fma_f32 v[206:207], v[112:113], v[222:223], v[206:207]
	global_store_dwordx4 v[244:245], v[206:209], off offset:64
	v_add_co_u32_e32 v236, vcc, 0x10200, v230
	v_addc_co_u32_e32 v237, vcc, 0, v231, vcc
	global_load_dwordx4 v[202:205], v[236:237], off
	global_load_dwordx4 v[206:209], v[236:237], off offset:64
	v_add_co_u32_e32 v244, vcc, 0x10000, v232
	v_addc_co_u32_e32 v245, vcc, 0, v233, vcc
	s_waitcnt vmcnt(4)
	v_pk_fma_f32 v[196:197], v[110:111], v[212:213], v[196:197]
	v_pk_fma_f32 v[194:195], v[108:109], v[210:211], v[194:195]
	global_store_dwordx4 v[244:245], v[194:197], off
	v_pk_fma_f32 v[200:201], v[106:107], v[216:217], v[200:201]
	v_pk_fma_f32 v[198:199], v[104:105], v[214:215], v[198:199]
	global_store_dwordx4 v[244:245], v[198:201], off offset:64
	v_add_co_u32_e32 v236, vcc, 0x20000, v230
	v_addc_co_u32_e32 v237, vcc, 0, v231, vcc
	global_load_dwordx4 v[194:197], v[236:237], off
	global_load_dwordx4 v[198:201], v[236:237], off offset:64
	v_add_co_u32_e32 v244, vcc, 0x10200, v232
	v_addc_co_u32_e32 v245, vcc, 0, v233, vcc
	s_waitcnt vmcnt(4)
	v_pk_fma_f32 v[204:205], v[102:103], v[220:221], v[204:205]
	v_pk_fma_f32 v[202:203], v[100:101], v[218:219], v[202:203]
	global_store_dwordx4 v[244:245], v[202:205], off
	v_pk_fma_f32 v[208:209], v[98:99], v[224:225], v[208:209]
	v_pk_fma_f32 v[206:207], v[96:97], v[222:223], v[206:207]
	global_store_dwordx4 v[244:245], v[206:209], off offset:64
	v_add_co_u32_e32 v236, vcc, 0x20200, v230
	v_addc_co_u32_e32 v237, vcc, 0, v231, vcc
	global_load_dwordx4 v[202:205], v[236:237], off
	global_load_dwordx4 v[206:209], v[236:237], off offset:64
	v_add_co_u32_e32 v244, vcc, 0x20000, v232
	v_addc_co_u32_e32 v245, vcc, 0, v233, vcc
	s_waitcnt vmcnt(4)
	v_pk_fma_f32 v[196:197], v[94:95], v[212:213], v[196:197]
	v_pk_fma_f32 v[194:195], v[92:93], v[210:211], v[194:195]
	global_store_dwordx4 v[244:245], v[194:197], off
	v_pk_fma_f32 v[200:201], v[90:91], v[216:217], v[200:201]
	v_pk_fma_f32 v[198:199], v[88:89], v[214:215], v[198:199]
	global_store_dwordx4 v[244:245], v[198:201], off offset:64
	v_add_co_u32_e32 v236, vcc, 0x30000, v230
	v_addc_co_u32_e32 v237, vcc, 0, v231, vcc
	global_load_dwordx4 v[194:197], v[236:237], off
	global_load_dwordx4 v[198:201], v[236:237], off offset:64
	v_add_co_u32_e32 v244, vcc, 0x20200, v232
	v_addc_co_u32_e32 v245, vcc, 0, v233, vcc
	s_waitcnt vmcnt(4)
	v_pk_fma_f32 v[204:205], v[86:87], v[220:221], v[204:205]
	v_pk_fma_f32 v[202:203], v[84:85], v[218:219], v[202:203]
	global_store_dwordx4 v[244:245], v[202:205], off
	v_pk_fma_f32 v[208:209], v[82:83], v[224:225], v[208:209]
	v_pk_fma_f32 v[206:207], v[80:81], v[222:223], v[206:207]
	global_store_dwordx4 v[244:245], v[206:209], off offset:64
	v_add_co_u32_e32 v236, vcc, 0x30200, v230
	v_addc_co_u32_e32 v237, vcc, 0, v231, vcc
	global_load_dwordx4 v[202:205], v[236:237], off
	global_load_dwordx4 v[206:209], v[236:237], off offset:64
	v_add_co_u32_e32 v244, vcc, 0x30000, v232
	v_addc_co_u32_e32 v245, vcc, 0, v233, vcc
	s_waitcnt vmcnt(4)
	v_pk_fma_f32 v[196:197], v[78:79], v[212:213], v[196:197]
	v_pk_fma_f32 v[194:195], v[76:77], v[210:211], v[194:195]
	global_store_dwordx4 v[244:245], v[194:197], off
	v_pk_fma_f32 v[200:201], v[74:75], v[216:217], v[200:201]
	v_pk_fma_f32 v[198:199], v[72:73], v[214:215], v[198:199]
	global_store_dwordx4 v[244:245], v[198:201], off offset:64
	v_add_co_u32_e32 v236, vcc, 0x80000, v230
	v_addc_co_u32_e32 v237, vcc, 0, v231, vcc
	global_load_dwordx4 v[194:197], v[236:237], off
	global_load_dwordx4 v[198:201], v[236:237], off offset:64
	v_add_co_u32_e32 v244, vcc, 0x30200, v232
	v_addc_co_u32_e32 v245, vcc, 0, v233, vcc
	s_waitcnt vmcnt(4)
	v_pk_fma_f32 v[204:205], v[70:71], v[220:221], v[204:205]
	v_pk_fma_f32 v[202:203], v[68:69], v[218:219], v[202:203]
	global_store_dwordx4 v[244:245], v[202:205], off
	v_pk_fma_f32 v[208:209], v[66:67], v[224:225], v[208:209]
	v_pk_fma_f32 v[206:207], v[64:65], v[222:223], v[206:207]
	global_store_dwordx4 v[244:245], v[206:209], off offset:64
	v_add_co_u32_e32 v236, vcc, 0x80200, v230
	v_addc_co_u32_e32 v237, vcc, 0, v231, vcc
	global_load_dwordx4 v[202:205], v[236:237], off
	global_load_dwordx4 v[206:209], v[236:237], off offset:64
	v_add_co_u32_e32 v244, vcc, 0x80000, v232
	v_addc_co_u32_e32 v245, vcc, 0, v233, vcc
	s_waitcnt vmcnt(4)
	v_pk_fma_f32 v[196:197], v[62:63], v[212:213], v[196:197]
	v_pk_fma_f32 v[194:195], v[60:61], v[210:211], v[194:195]
	global_store_dwordx4 v[244:245], v[194:197], off
	v_pk_fma_f32 v[200:201], v[58:59], v[216:217], v[200:201]
	v_pk_fma_f32 v[198:199], v[56:57], v[214:215], v[198:199]
	global_store_dwordx4 v[244:245], v[198:201], off offset:64
	v_add_co_u32_e32 v236, vcc, 0x90000, v230
	v_addc_co_u32_e32 v237, vcc, 0, v231, vcc
	global_load_dwordx4 v[194:197], v[236:237], off
	global_load_dwordx4 v[198:201], v[236:237], off offset:64
	v_add_co_u32_e32 v244, vcc, 0x80200, v232
	v_addc_co_u32_e32 v245, vcc, 0, v233, vcc
	s_waitcnt vmcnt(4)
	v_pk_fma_f32 v[204:205], v[54:55], v[220:221], v[204:205]
	v_pk_fma_f32 v[202:203], v[52:53], v[218:219], v[202:203]
	global_store_dwordx4 v[244:245], v[202:205], off
	v_pk_fma_f32 v[208:209], v[50:51], v[224:225], v[208:209]
	v_pk_fma_f32 v[206:207], v[48:49], v[222:223], v[206:207]
	global_store_dwordx4 v[244:245], v[206:209], off offset:64
	v_add_co_u32_e32 v236, vcc, 0x90200, v230
	v_addc_co_u32_e32 v237, vcc, 0, v231, vcc
	global_load_dwordx4 v[202:205], v[236:237], off
	global_load_dwordx4 v[206:209], v[236:237], off offset:64
	v_add_co_u32_e32 v244, vcc, 0x90000, v232
	v_addc_co_u32_e32 v245, vcc, 0, v233, vcc
	s_waitcnt vmcnt(4)
	v_pk_fma_f32 v[196:197], v[46:47], v[212:213], v[196:197]
	v_pk_fma_f32 v[194:195], v[44:45], v[210:211], v[194:195]
	global_store_dwordx4 v[244:245], v[194:197], off
	v_pk_fma_f32 v[200:201], v[42:43], v[216:217], v[200:201]
	v_pk_fma_f32 v[198:199], v[40:41], v[214:215], v[198:199]
	global_store_dwordx4 v[244:245], v[198:201], off offset:64
	v_add_co_u32_e32 v236, vcc, 0xa0000, v230
	v_addc_co_u32_e32 v237, vcc, 0, v231, vcc
	global_load_dwordx4 v[194:197], v[236:237], off
	global_load_dwordx4 v[198:201], v[236:237], off offset:64
	v_add_co_u32_e32 v244, vcc, 0x90200, v232
	v_addc_co_u32_e32 v245, vcc, 0, v233, vcc
	s_waitcnt vmcnt(4)
	v_pk_fma_f32 v[204:205], v[38:39], v[220:221], v[204:205]
	v_pk_fma_f32 v[202:203], v[36:37], v[218:219], v[202:203]
	global_store_dwordx4 v[244:245], v[202:205], off
	v_pk_fma_f32 v[208:209], v[34:35], v[224:225], v[208:209]
	v_pk_fma_f32 v[206:207], v[32:33], v[222:223], v[206:207]
	global_store_dwordx4 v[244:245], v[206:209], off offset:64
	v_add_co_u32_e32 v236, vcc, 0xa0200, v230
	v_addc_co_u32_e32 v237, vcc, 0, v231, vcc
	global_load_dwordx4 v[202:205], v[236:237], off
	global_load_dwordx4 v[206:209], v[236:237], off offset:64
	v_add_co_u32_e32 v244, vcc, 0xa0000, v232
	v_addc_co_u32_e32 v245, vcc, 0, v233, vcc
	s_waitcnt vmcnt(4)
	v_pk_fma_f32 v[196:197], v[30:31], v[212:213], v[196:197]
	v_pk_fma_f32 v[194:195], v[28:29], v[210:211], v[194:195]
	global_store_dwordx4 v[244:245], v[194:197], off
	v_pk_fma_f32 v[200:201], v[26:27], v[216:217], v[200:201]
	v_pk_fma_f32 v[198:199], v[24:25], v[214:215], v[198:199]
	global_store_dwordx4 v[244:245], v[198:201], off offset:64
	v_add_co_u32_e32 v236, vcc, 0xb0000, v230
	v_addc_co_u32_e32 v237, vcc, 0, v231, vcc
	global_load_dwordx4 v[194:197], v[236:237], off
	global_load_dwordx4 v[198:201], v[236:237], off offset:64
	v_add_co_u32_e32 v244, vcc, 0xa0200, v232
	v_addc_co_u32_e32 v245, vcc, 0, v233, vcc
	s_waitcnt vmcnt(4)
	v_pk_fma_f32 v[204:205], v[22:23], v[220:221], v[204:205]
	v_pk_fma_f32 v[202:203], v[20:21], v[218:219], v[202:203]
	global_store_dwordx4 v[244:245], v[202:205], off
	v_pk_fma_f32 v[208:209], v[18:19], v[224:225], v[208:209]
	v_pk_fma_f32 v[206:207], v[16:17], v[222:223], v[206:207]
	global_store_dwordx4 v[244:245], v[206:209], off offset:64
	v_add_co_u32_e32 v236, vcc, 0xb0200, v230
	v_addc_co_u32_e32 v237, vcc, 0, v231, vcc
	global_load_dwordx4 v[202:205], v[236:237], off
	global_load_dwordx4 v[206:209], v[236:237], off offset:64
	v_add_co_u32_e32 v244, vcc, 0xb0000, v232
	v_addc_co_u32_e32 v245, vcc, 0, v233, vcc
	s_waitcnt vmcnt(4)
	v_pk_fma_f32 v[196:197], v[14:15], v[212:213], v[196:197]
	v_pk_fma_f32 v[194:195], v[12:13], v[210:211], v[194:195]
	global_store_dwordx4 v[244:245], v[194:197], off
	v_pk_fma_f32 v[200:201], v[10:11], v[216:217], v[200:201]
	v_pk_fma_f32 v[198:199], v[8:9], v[214:215], v[198:199]
	global_store_dwordx4 v[244:245], v[198:201], off offset:64
	v_add_co_u32_e32 v244, vcc, 0xb0200, v232
	v_addc_co_u32_e32 v245, vcc, 0, v233, vcc
	s_waitcnt vmcnt(2)
	v_pk_fma_f32 v[204:205], v[6:7], v[220:221], v[204:205]
	v_pk_fma_f32 v[202:203], v[4:5], v[218:219], v[202:203]
	global_store_dwordx4 v[244:245], v[202:205], off
	v_pk_fma_f32 v[208:209], v[2:3], v[224:225], v[208:209]
	v_pk_fma_f32 v[206:207], v[0:1], v[222:223], v[206:207]
	global_store_dwordx4 v[244:245], v[206:209], off offset:64
	s_or_b64 exec, exec, s[60:61]
	s_movk_i32 s83, 0xff
	s_branch .LBB0_1065
